# scan: V chunk staged by the consumer waves via LDS-DMA one iteration ahead (16B swizzle), producer drops 4 loads + 8 LDS writes per chunk
# speedup vs baseline: 1.2630x; 1.0093x over previous
.LBB0_280:
	s_or_b64 exec, exec, s[0:1]
	v_readlane_b32 s8, v251, 39
	v_readlane_b32 s9, v251, 40
	s_ashr_i32 s14, s15, 6
	v_and_b32_e32 v174, 63, v161
	v_cndmask_b32_e64 v1, 0, 1, s[8:9]
	v_and_b32_e32 v0, 15, v161
	v_bfe_u32 v47, v161, 4, 2
	s_mov_b64 s[0:1], -1
	s_cmp_lt_i32 s14, 4
	v_cmp_ne_u32_e64 s[38:39], 1, v1
	s_cbranch_scc1 .LBB0_312
	s_and_b64 vcc, exec, s[38:39]
	s_cbranch_vccnz .LBB0_311
	v_add_u32_e32 v53, 0xffffff00, v161
	v_ashrrev_i32_e32 v175, 3, v53
	s_movk_i32 s0, 0x410
	v_lshl_or_b32 v1, s14, 4, v0
	s_waitcnt lgkmcnt(0)
	v_mul_lo_u32 v3, v175, s0
	v_readlane_b32 s0, v254, 38
	s_waitcnt vmcnt(0)
	v_subrev_u32_e32 v6, 64, v1
	v_and_b32_e32 v1, 7, v161
	v_add_u32_e32 v7, s0, v3
	v_readlane_b32 s0, v253, 53
	v_lshlrev_b32_e32 v4, 4, v1
	v_mov_b32_e32 v5, v2
	v_readlane_b32 s1, v253, 54
	v_lshlrev_b32_e32 v176, 3, v47
	v_lshlrev_b32_e32 v9, 1, v161
	v_lshl_add_u64 v[36:37], s[0:1], 0, v[4:5]
	v_readlane_b32 s0, v251, 22
	v_readlane_b32 s1, v251, 23
	v_lshlrev_b32_e32 v8, 5, v1
	v_lshl_add_u32 v177, v53, 6, 0
	v_lshl_add_u64 v[38:39], s[0:1], 0, v[4:5]
	s_movk_i32 s0, 0xa0
	v_mul_lo_u32 v5, v6, s0
	s_movk_i32 s0, 0xff68
	v_add_u32_e32 v185, 0, v5
	v_mul_lo_u32 v186, v6, s0
	v_lshlrev_b32_e32 v4, 2, v6
	v_add_u32_e32 v187, v185, v186
	v_sub_u32_e32 v46, v187, v4
	s_movk_i32 s0, 0x9c
	v_or_b32_e32 v40, 2, v176
	v_or_b32_e32 v3, 3, v176
	v_or_b32_e32 v43, 4, v176
	v_or_b32_e32 v42, 5, v176
	v_or_b32_e32 v45, 6, v176
	v_or_b32_e32 v44, 7, v176
	v_and_b32_e32 v180, 24, v9
	v_bitop3_b32 v181, v9, 8, 24 bitop3:0x6c
	v_bitop3_b32 v182, v9, 16, 24 bitop3:0x6c
	v_bitop3_b32 v183, v9, 24, v9 bitop3:0xc
	v_add_u32_e32 v9, 0, v4
	v_mul_u32_u24_e32 v184, 0x840, v47
	v_mad_u64_u32 v[48:49], s[0:1], v6, s0, v[46:47]
	v_lshlrev_b32_e32 v55, 1, v6
	v_add_u32_e32 v178, 0xd800, v177
	v_cmp_gt_u32_e64 s[40:41], 16, v174
	v_cmp_lt_u32_e64 s[42:43], 31, v174
	v_and_b32_e32 v179, 48, v161
	v_or_b32_e32 v1, 1, v176
	v_pk_mov_b32 v[50:51], v[44:45], v[42:43] op_sel:[1,0]
	v_mov_b32_e32 v52, v43
	v_mov_b32_e32 v54, v3
	v_mov_b32_e32 v41, v40
	v_add_u32_e32 v49, v9, v184
	v_add_u32_e32 v188, v7, v8
	s_mov_b32 s16, s2
	s_branch .LBB0_284

.LBB0_288:
	s_add_i32 s0, s17, 31
	s_lshr_b32 s18, s0, 5
	s_add_i32 s0, s18, 3
	s_and_b32 s19, s0, 0x46
	s_cmp_eq_u32 s19, 0
	s_cbranch_scc1 .LBB0_283
	s_and_b32 s0, s16, 15
	s_add_i32 s20, s18, -1
	s_ashr_i32 s9, s8, 31
	s_cmp_eq_u32 s20, 0
	v_add_u32_e32 v56, s8, v176
	s_cselect_b32 s1, 0, 32
	s_waitcnt vmcnt(0)
	v_add_u32_e32 v20, s1, v56
	v_ashrrev_i32_e32 v21, 31, v20
	v_lshl_add_u32 v58, s0, 7, v55
	v_mov_b32_e32 v59, v2
	v_lshlrev_b64 v[20:21], 11, v[20:21]
	v_lshl_add_u64 v[20:21], v[20:21], 0, v[58:59]
	v_lshlrev_b64 v[22:23], 1, v[20:21]
	v_lshl_add_u64 v[24:25], s[72:73], 0, v[22:23]
	v_add_co_u32_e32 v26, vcc, s33, v24
	v_lshl_add_u64 v[22:23], s[64:65], 0, v[22:23]
	s_nop 0
	v_addc_co_u32_e32 v27, vcc, 0, v25, vcc
	v_add_co_u32_e32 v28, vcc, s33, v22
	v_lshl_add_u64 v[20:21], v[20:21], 2, s[74:75]
	s_nop 0
	v_addc_co_u32_e32 v29, vcc, 0, v23, vcc
	s_mov_b32 s3, 0xe000
	v_add_co_u32_e32 v30, vcc, s3, v20
	v_readlane_b32 s10, v251, 37
	s_nop 0
	v_addc_co_u32_e32 v31, vcc, 0, v21, vcc
	v_readlane_b32 s11, v251, 38
	v_add_co_u32_e32 v32, vcc, s63, v24
	v_lshl_add_u32 v6, s0, 8, v53
	v_mov_b64_e32 v[4:5], s[10:11]
	v_addc_co_u32_e32 v33, vcc, 0, v25, vcc
	v_mad_i64_i32 v[4:5], s[10:11], v6, s93, v[4:5]
	v_add_co_u32_e32 v34, vcc, s63, v22
	v_readlane_b32 s10, v253, 63
	s_nop 0
	v_addc_co_u32_e32 v35, vcc, 0, v23, vcc
	v_lshl_add_u64 v[60:61], s[8:9], 1, v[4:5]
	v_readlane_b32 s11, v254, 0
	s_lshl_b32 s10, s1, 1
	v_add_co_u32_e32 v62, vcc, s67, v20
	v_lshl_add_u64 v[16:17], v[60:61], 0, s[10:11]
	s_nop 0
	v_addc_co_u32_e32 v63, vcc, 0, v21, vcc
	s_movk_i32 s10, 0x5000
	s_nop 0
	s_nop 0
	global_load_dwordx2 v[64:65], v[30:31], off
	global_load_dword v196, v[32:33], off
	global_load_dword v189, v[34:35], off
	global_load_dwordx2 v[66:67], v[62:63], off
	v_add_co_u32_e32 v30, vcc, s10, v24
	s_mov_b32 s9, 0xa000
	s_nop 0
	v_addc_co_u32_e32 v31, vcc, 0, v25, vcc
	v_add_co_u32_e32 v32, vcc, s10, v22
	s_mov_b32 s1, 0x8000
	s_nop 0
	v_addc_co_u32_e32 v33, vcc, 0, v23, vcc
	v_add_co_u32_e32 v34, vcc, s9, v20
	s_movk_i32 s12, 0x3000
	s_nop 0
	v_addc_co_u32_e32 v35, vcc, 0, v21, vcc
	v_add_co_u32_e32 v68, vcc, s66, v24
	s_movk_i32 s13, 0x1000
	s_nop 0
	v_addc_co_u32_e32 v69, vcc, 0, v25, vcc
	v_add_co_u32_e32 v70, vcc, s66, v22
	v_ashrrev_i32_e32 v57, 31, v56
	s_nop 0
	v_addc_co_u32_e32 v71, vcc, 0, v23, vcc
	global_load_dword v198, v[30:31], off
	global_load_dword v192, v[32:33], off
	global_load_dwordx2 v[62:63], v[34:35], off
	global_load_dword v197, v[68:69], off
	global_load_dword v190, v[70:71], off
	v_add_co_u32_e32 v30, vcc, s1, v20
	v_lshlrev_b64 v[78:79], 11, v[56:57]
	s_nop 0
	v_addc_co_u32_e32 v31, vcc, 0, v21, vcc
	v_add_co_u32_e32 v32, vcc, s12, v24
	v_lshl_add_u64 v[78:79], v[78:79], 0, v[58:59]
	s_nop 0
	v_addc_co_u32_e32 v33, vcc, 0, v25, vcc
	v_add_co_u32_e32 v34, vcc, s12, v22
	v_lshlrev_b64 v[80:81], 1, v[78:79]
	s_nop 0
	v_addc_co_u32_e32 v35, vcc, 0, v23, vcc
	v_add_co_u32_e32 v68, vcc, s63, v20
	v_lshl_add_u64 v[82:83], s[72:73], 0, v[80:81]
	s_nop 0
	v_addc_co_u32_e32 v69, vcc, 0, v21, vcc
	global_load_dwordx2 v[70:71], v[30:31], off
	global_load_dword v200, v[32:33], off
	global_load_dword v191, v[34:35], off
	global_load_dwordx2 v[72:73], v[68:69], off
	v_add_co_u32_e32 v30, vcc, s69, v24
	v_lshl_add_u64 v[80:81], s[64:65], 0, v[80:81]
	s_nop 0
	v_addc_co_u32_e32 v31, vcc, 0, v25, vcc
	v_add_co_u32_e32 v32, vcc, s69, v22
	v_lshl_add_u64 v[78:79], v[78:79], 2, s[74:75]
	s_nop 0
	v_addc_co_u32_e32 v33, vcc, 0, v23, vcc
	v_add_co_u32_e32 v34, vcc, s66, v20
	v_xor_b32_e32 v57, 1, v208
	s_nop 0
	v_addc_co_u32_e32 v35, vcc, 0, v21, vcc
	v_add_co_u32_e32 v68, vcc, s13, v24
	s_mov_b32 s28, 0xe000
	s_nop 0
	v_addc_co_u32_e32 v69, vcc, 0, v25, vcc
	v_add_co_u32_e32 v74, vcc, s13, v22
	s_mov_b32 s47, 0x8000
	s_nop 0
	v_addc_co_u32_e32 v75, vcc, 0, v23, vcc
	global_load_dword v202, v[30:31], off
	global_load_dword v195, v[32:33], off
	global_load_dwordx2 v[76:77], v[34:35], off
	global_load_dword v215, v[68:69], off
	global_load_dword v194, v[74:75], off
	v_add_co_u32_e32 v74, vcc, s69, v20
	s_mov_b32 s24, 0
	s_nop 0
	v_addc_co_u32_e32 v75, vcc, 0, v21, vcc
	v_add_co_u32_e32 v84, vcc, s33, v82
	global_load_dword v225, v[26:27], off
	global_load_dword v199, v[28:29], off
	global_load_dwordx2 v[68:69], v[20:21], off
	global_load_dword v193, v[22:23], off
	global_load_dword v201, v[24:25], off
	s_nop 0
	v_addc_co_u32_e32 v85, vcc, 0, v83, vcc
	v_add_co_u32_e32 v86, vcc, s33, v80
	v_add_u32_e32 v217, s8, v175
	s_nop 0
	v_addc_co_u32_e32 v87, vcc, 0, v81, vcc
	v_add_co_u32_e32 v88, vcc, s3, v78
	s_mov_b32 s3, 0xa000
	s_nop 0
	v_addc_co_u32_e32 v89, vcc, 0, v79, vcc
	v_add_co_u32_e32 v92, vcc, s63, v82
	s_add_i32 s21, s8, 32
	s_nop 0
	v_addc_co_u32_e32 v93, vcc, 0, v83, vcc
	v_add_co_u32_e32 v94, vcc, s63, v80
	s_sub_i32 s22, s17, 32
	s_nop 0
	v_addc_co_u32_e32 v95, vcc, 0, v81, vcc
	v_add_co_u32_e32 v90, vcc, s67, v78
	v_mov_b32_e32 v112, 0
	s_nop 0
	v_addc_co_u32_e32 v91, vcc, 0, v79, vcc
	v_add_co_u32_e32 v96, vcc, s10, v82
	v_mov_b32_e32 v113, 0
	s_nop 0
	v_addc_co_u32_e32 v97, vcc, 0, v83, vcc
	v_add_co_u32_e32 v98, vcc, s10, v80
	s_lshl_b32 s10, s0, 9
	s_nop 0
	v_addc_co_u32_e32 v99, vcc, 0, v81, vcc
	v_add_co_u32_e32 v100, vcc, s9, v78
	s_mov_b32 s9, 1
	s_nop 0
	v_addc_co_u32_e32 v101, vcc, 0, v79, vcc
	global_load_dwordx2 v[108:109], v[90:91], off
	global_load_dword v229, v[96:97], off
	global_load_dword v221, v[98:99], off
	s_nop 0
	global_load_dwordx2 v[90:91], v[100:101], off
	v_add_co_u32_e32 v96, vcc, s66, v82
	v_mov_b32_e32 v120, 0
	s_nop 0
	v_addc_co_u32_e32 v97, vcc, 0, v83, vcc
	v_add_co_u32_e32 v98, vcc, s66, v80
	v_mov_b32_e32 v121, 0
	s_nop 0
	v_addc_co_u32_e32 v99, vcc, 0, v81, vcc
	v_add_co_u32_e32 v100, vcc, s1, v78
	s_mov_b32 s1, s11
	s_nop 0
	v_addc_co_u32_e32 v101, vcc, 0, v79, vcc
	v_add_co_u32_e32 v102, vcc, s12, v82
	v_writelane_b32 v253, s0, 63
	s_nop 0
	v_addc_co_u32_e32 v103, vcc, 0, v83, vcc
	v_add_co_u32_e32 v104, vcc, s12, v80
	v_writelane_b32 v254, s1, 0
	s_nop 0
	v_addc_co_u32_e32 v105, vcc, 0, v81, vcc
	global_load_dword v231, v[96:97], off
	global_load_dword v223, v[98:99], off
	s_nop 0
	global_load_dwordx2 v[100:101], v[100:101], off
	s_nop 0
	global_load_dword v232, v[102:103], off
	global_load_dword v222, v[104:105], off
	v_add_co_u32_e32 v96, vcc, s63, v78
	v_mov_b32_e32 v124, 0
	s_nop 0
	v_addc_co_u32_e32 v97, vcc, 0, v79, vcc
	v_add_co_u32_e32 v98, vcc, s69, v82
	v_mov_b32_e32 v125, 0
	s_nop 0
	v_addc_co_u32_e32 v99, vcc, 0, v83, vcc
	v_add_co_u32_e32 v102, vcc, s69, v80
	v_mov_b32_e32 v110, 0
	s_nop 0
	v_addc_co_u32_e32 v103, vcc, 0, v81, vcc
	v_add_co_u32_e32 v104, vcc, s66, v78
	v_mov_b32_e32 v111, 0
	s_nop 0
	v_addc_co_u32_e32 v105, vcc, 0, v79, vcc
	global_load_dwordx2 v[114:115], v[96:97], off
	global_load_dword v234, v[98:99], off
	global_load_dword v226, v[102:103], off
	global_load_dwordx2 v[118:119], v[104:105], off
	v_add_co_u32_e32 v96, vcc, s13, v82
	v_mov_b32_e32 v116, 0
	s_nop 0
	v_addc_co_u32_e32 v97, vcc, 0, v83, vcc
	v_add_co_u32_e32 v98, vcc, s13, v80
	v_mov_b32_e32 v117, 0
	s_nop 0
	v_addc_co_u32_e32 v99, vcc, 0, v81, vcc
	v_add_co_u32_e32 v102, vcc, s69, v78
	v_mov_b32_e32 v122, 0
	s_nop 0
	v_addc_co_u32_e32 v103, vcc, 0, v79, vcc
	global_load_dword v235, v[96:97], off
	global_load_dword v227, v[98:99], off
	s_nop 0
	global_load_dwordx2 v[102:103], v[102:103], off
	s_nop 0
	global_load_dwordx2 v[104:105], v[74:75], off
	global_load_dword v237, v[84:85], off
	global_load_dword v230, v[86:87], off
	global_load_dword v224, v[80:81], off
	global_load_dword v233, v[82:83], off
	global_load_dwordx2 v[128:129], v[88:89], off
	global_load_dword v236, v[92:93], off
	global_load_dword v228, v[94:95], off
	global_load_dwordx2 v[106:107], v[78:79], off
	v_and_b32_e32 v80, 64, v208
	v_add_u32_e32 v74, 64, v80
	v_cmp_lt_i32_e32 vcc, v57, v74
	v_xor_b32_e32 v75, 2, v208
	v_add_u32_e32 v81, -16, v208
	v_cndmask_b32_e32 v57, v208, v57, vcc
	v_cmp_lt_i32_e32 vcc, v75, v74
	v_lshlrev_b32_e32 v57, 2, v57
	v_lshl_add_u64 v[78:79], v[38:39], 0, s[10:11]
	v_cndmask_b32_e32 v75, v208, v75, vcc
	v_lshlrev_b32_e32 v203, 2, v75
	v_xor_b32_e32 v75, 4, v208
	v_cmp_lt_i32_e32 vcc, v75, v74
	v_mov_b32_e32 v84, 0
	v_mov_b32_e32 v85, 0
	v_cndmask_b32_e32 v74, v208, v75, vcc
	v_cmp_lt_i32_e32 vcc, v81, v80
	v_lshlrev_b32_e32 v216, 2, v74
	v_lshl_add_u64 v[74:75], v[36:37], 0, s[10:11]
	v_cndmask_b32_e32 v81, v81, v208, vcc
	v_lshlrev_b32_e32 v218, 2, v81
	v_subrev_u32_e32 v81, 32, v208
	v_cmp_lt_i32_e32 vcc, v81, v80
	v_or_b32_e32 v80, v80, v0
	v_lshl_or_b32 v220, v80, 2, v209
	v_cndmask_b32_e32 v81, v81, v208, vcc
	v_lshlrev_b32_e32 v219, 2, v81
	v_mov_b32_e32 v80, 0
	v_mov_b32_e32 v81, 0
	v_mov_b32_e32 v88, 0
	v_mov_b32_e32 v89, 0
	v_mov_b32_e32 v94, 0
	v_mov_b32_e32 v95, 0
	v_mov_b32_e32 v98, 0
	v_mov_b32_e32 v99, 0
	v_mov_b32_e32 v82, 0
	v_mov_b32_e32 v83, 0
	v_mov_b32_e32 v86, 0
	v_mov_b32_e32 v87, 0
	v_mov_b32_e32 v92, 0
	v_mov_b32_e32 v93, 0
	v_mov_b32_e32 v96, 0
	v_mov_b32_e32 v97, 0
	v_mov_b32_e32 v123, 0
	v_mov_b32_e32 v126, 0
	v_mov_b32_e32 v127, 0
	s_mov_b32 s23, s17
	s_branch .LBB0_291

.LBB0_299:
	s_add_i32 s25, s24, 2
	s_min_i32 s0, s25, s20
	s_lshl_b32 s0, s0, 5
	v_add_u32_e32 v20, s0, v56
	v_ashrrev_i32_e32 v21, 31, v20
	v_lshlrev_b64 v[20:21], 11, v[20:21]
	v_lshl_add_u64 v[20:21], v[20:21], 0, v[58:59]
	v_lshl_add_u64 v[22:23], v[20:21], 2, s[74:75]
	v_lshlrev_b64 v[20:21], 1, v[20:21]
	v_add_co_u32_e32 v26, vcc, s69, v22
	v_lshl_add_u64 v[24:25], s[64:65], 0, v[20:21]
	s_nop 0
	v_addc_co_u32_e32 v27, vcc, 0, v23, vcc
	v_lshlrev_b32_e32 v244, 16, v224
	v_and_b32_e32 v245, 0xffff0000, v224
	v_lshl_add_u64 v[20:21], s[72:73], 0, v[20:21]
	global_load_dwordx2 v[106:107], v[22:23], off
	global_load_dword v224, v[24:25], off
	global_load_dword v233, v[20:21], off
	global_load_dwordx2 v[102:103], v[26:27], off
	v_add_co_u32_e32 v26, vcc, s69, v24
	v_lshlrev_b32_e32 v246, 16, v227
	s_nop 0
	v_addc_co_u32_e32 v27, vcc, 0, v25, vcc
	v_add_co_u32_e32 v28, vcc, s69, v20
	v_and_b32_e32 v247, 0xffff0000, v227
	s_nop 0
	v_addc_co_u32_e32 v29, vcc, 0, v21, vcc
	v_add_co_u32_e32 v30, vcc, s66, v22
	v_lshlrev_b32_e32 v248, 16, v226
	s_nop 0
	v_addc_co_u32_e32 v31, vcc, 0, v23, vcc
	v_add_co_u32_e32 v32, vcc, s66, v24
	v_and_b32_e32 v249, 0xffff0000, v226
	s_nop 0
	v_addc_co_u32_e32 v33, vcc, 0, v25, vcc
	v_add_co_u32_e32 v34, vcc, s66, v20
	v_lshlrev_b32_e32 v172, 16, v222
	s_nop 0
	v_addc_co_u32_e32 v35, vcc, 0, v21, vcc
	v_and_b32_e32 v173, 0xffff0000, v222
	v_lshlrev_b32_e32 v170, 16, v223
	v_and_b32_e32 v171, 0xffff0000, v223
	global_load_dword v227, v[26:27], off offset:-4096
	global_load_dword v235, v[28:29], off offset:-4096
	global_load_dword v234, v[28:29], off
	global_load_dword v222, v[32:33], off offset:-4096
	global_load_dword v232, v[34:35], off offset:-4096
	global_load_dword v231, v[34:35], off
	global_load_dword v223, v[32:33], off
	global_load_dword v226, v[26:27], off
	v_add_co_u32_e32 v26, vcc, s63, v22
	v_lshlrev_b32_e32 v168, 16, v221
	s_nop 0
	v_addc_co_u32_e32 v27, vcc, 0, v23, vcc
	v_add_co_u32_e32 v28, vcc, s47, v22
	v_and_b32_e32 v169, 0xffff0000, v221
	s_nop 0
	v_addc_co_u32_e32 v29, vcc, 0, v23, vcc
	v_add_co_u32_e32 v32, vcc, s3, v22
	v_lshlrev_b32_e32 v166, 16, v228
	s_nop 0
	v_addc_co_u32_e32 v33, vcc, 0, v23, vcc
	global_load_dwordx2 v[118:119], v[30:31], off
	global_load_dwordx2 v[114:115], v[26:27], off
	global_load_dwordx2 v[100:101], v[28:29], off
	global_load_dwordx2 v[90:91], v[32:33], off
	v_add_co_u32_e32 v26, vcc, s63, v24
	v_and_b32_e32 v167, 0xffff0000, v228
	s_nop 0
	v_addc_co_u32_e32 v27, vcc, 0, v25, vcc
	v_add_co_u32_e32 v28, vcc, s63, v20
	s_ashr_i32 s1, s0, 31
	s_nop 0
	v_addc_co_u32_e32 v29, vcc, 0, v21, vcc
	v_add_co_u32_e32 v30, vcc, s67, v22
	global_load_dword v221, v[26:27], off offset:-4096
	global_load_dword v229, v[28:29], off offset:-4096
	global_load_dword v236, v[28:29], off
	global_load_dword v228, v[26:27], off
	v_addc_co_u32_e32 v31, vcc, 0, v23, vcc
	v_add_co_u32_e32 v22, vcc, s28, v22
	ds_bpermute_b32 v26, v218, v134
	s_nop 0
	v_addc_co_u32_e32 v23, vcc, 0, v23, vcc
	ds_bpermute_b32 v27, v218, v137
	v_add_co_u32_e32 v24, vcc, s33, v24
	v_lshlrev_b32_e32 v158, 16, v230
	s_nop 0
	v_addc_co_u32_e32 v25, vcc, 0, v25, vcc
	v_add_co_u32_e32 v20, vcc, s33, v20
	v_and_b32_e32 v159, 0xffff0000, v230
	s_nop 0
	v_addc_co_u32_e32 v21, vcc, 0, v21, vcc
	global_load_dwordx2 v[108:109], v[30:31], off
	global_load_dwordx2 v[128:129], v[22:23], off
	global_load_dword v230, v[24:25], off
	global_load_dword v237, v[20:21], off
	s_waitcnt lgkmcnt(1)
	v_add_f32_e32 v20, v134, v26
	s_waitcnt lgkmcnt(0)
	v_add_f32_e32 v21, v137, v27
	v_cndmask_b32_e64 v162, v20, v134, s[40:41]
	v_cndmask_b32_e64 v163, v21, v137, s[40:41]
	s_nop 0
	ds_bpermute_b32 v242, v219, v162
	ds_bpermute_b32 v243, v219, v163
	s_waitcnt lgkmcnt(1)
	v_add_f32_e32 v242, v162, v242
	s_waitcnt lgkmcnt(0)
	v_add_f32_e32 v243, v163, v243
	v_cndmask_b32_e64 v162, v162, v242, s[42:43]
	v_cndmask_b32_e64 v243, v163, v243, s[42:43]
	v_sub_f32_e32 v250, v162, v134
	v_sub_f32_e32 v211, v243, v137
	v_add_f32_e32 v207, v136, v250
	v_add_f32_e32 v139, v139, v211
	ds_bpermute_b32 v242, v220, v162
	v_exp_f32_e32 v162, v207
	v_exp_f32_e32 v163, v139
	v_exp_f32_e64 v207, -v207
	v_exp_f32_e64 v139, -v139
	v_add_f32_e32 v147, v147, v211
	v_pk_mul_f32 v[162:163], v[162:163], v[244:245]
	v_mul_f32_e32 v131, v131, v207
	v_add_f32_e32 v207, v138, v250
	v_cvt_pk_bf16_f32 v162, v162, v163
	v_mul_f32_e32 v163, v241, v139
	v_exp_f32_e32 v138, v207
	v_exp_f32_e32 v139, v147
	v_cvt_pk_bf16_f32 v163, v131, v163
	v_exp_f32_e64 v131, -v207
	v_exp_f32_e64 v147, -v147
	v_pk_mul_f32 v[138:139], v[138:139], v[246:247]
	v_add_f32_e32 v146, v146, v250
	v_cvt_pk_bf16_f32 v138, v138, v139
	v_mul_f32_e32 v131, v239, v131
	v_mul_f32_e32 v139, v240, v147
	v_add_f32_e32 v147, v149, v211
	v_cvt_pk_bf16_f32 v207, v131, v139
	ds_write2_b32 v49, v162, v138 offset1:66
	v_exp_f32_e32 v138, v146
	v_exp_f32_e32 v139, v147
	v_exp_f32_e64 v146, -v146
	v_exp_f32_e64 v147, -v147
	v_add_u32_e32 v131, 0x2000, v49
	v_pk_mul_f32 v[138:139], v[138:139], v[248:249]
	v_add_f32_e32 v148, v148, v250
	v_add_f32_e32 v143, v143, v211
	ds_write2_b32 v131, v163, v207 offset0:64 offset1:130
	v_cvt_pk_bf16_f32 v131, v138, v139
	v_pk_mul_f32 v[138:139], v[156:157], v[146:147]
	v_exp_f32_e32 v146, v148
	v_exp_f32_e32 v147, v143
	v_exp_f32_e64 v148, -v148
	v_exp_f32_e64 v149, -v143
	v_cvt_pk_bf16_f32 v156, v138, v139
	v_pk_mul_f32 v[138:139], v[146:147], v[172:173]
	v_add_f32_e32 v142, v142, v250
	v_cvt_pk_bf16_f32 v143, v138, v139
	v_pk_mul_f32 v[138:139], v[154:155], v[148:149]
	ds_write2_b32 v49, v131, v143 offset0:132 offset1:198
	v_add_f32_e32 v143, v145, v211
	v_cvt_pk_bf16_f32 v146, v138, v139
	v_exp_f32_e32 v138, v142
	v_exp_f32_e32 v139, v143
	v_exp_f32_e64 v142, -v142
	v_exp_f32_e64 v143, -v143
	v_add_u32_e32 v131, 0x2200, v49
	v_pk_mul_f32 v[138:139], v[138:139], v[170:171]
	v_add_f32_e32 v144, v144, v250
	v_add_f32_e32 v141, v141, v211
	ds_write2_b32 v131, v156, v146 offset0:68 offset1:134
	v_cvt_pk_bf16_f32 v131, v138, v139
	v_pk_mul_f32 v[138:139], v[152:153], v[142:143]
	v_exp_f32_e32 v142, v144
	v_exp_f32_e32 v143, v141
	v_exp_f32_e64 v144, -v144
	v_exp_f32_e64 v145, -v141
	v_cvt_pk_bf16_f32 v147, v138, v139
	v_pk_mul_f32 v[138:139], v[142:143], v[168:169]
	v_add_u32_e32 v143, 0x400, v49
	v_cvt_pk_bf16_f32 v141, v138, v139
	v_pk_mul_f32 v[138:139], v[150:151], v[144:145]
	v_add_f32_e32 v140, v140, v250
	v_add_f32_e32 v135, v135, v211
	v_cvt_pk_bf16_f32 v142, v138, v139
	ds_write2_b32 v143, v131, v141 offset0:8 offset1:74
	v_exp_f32_e32 v138, v140
	v_exp_f32_e32 v139, v135
	v_exp_f32_e64 v140, -v140
	v_exp_f32_e64 v141, -v135
	v_add_u32_e32 v131, 0x2400, v49
	ds_write2_b32 v131, v147, v142 offset0:72 offset1:138
	v_mov_b32_e32 v131, v133
	v_pk_mul_f32 v[138:139], v[138:139], v[166:167]
	v_pk_mul_f32 v[130:131], v[130:131], v[140:141]
	v_add_f32_e32 v133, v134, v250
	v_add_f32_e32 v137, v137, v211
	v_cvt_pk_bf16_f32 v138, v138, v139
	v_exp_f32_e32 v134, v133
	v_exp_f32_e32 v135, v137
	v_cvt_pk_bf16_f32 v139, v130, v131
	v_exp_f32_e64 v130, -v133
	v_exp_f32_e64 v131, -v137
	ds_bpermute_b32 v136, v220, v243
	v_mov_b32_e32 v133, v238
	v_pk_mul_f32 v[134:135], v[134:135], v[158:159]
	v_pk_mul_f32 v[130:131], v[132:133], v[130:131]
	v_cvt_pk_bf16_f32 v134, v134, v135
	v_cvt_pk_bf16_f32 v135, v130, v131
	v_add_u32_e32 v130, 0x2600, v49
	ds_write2_b32 v143, v138, v134 offset0:140 offset1:206
	ds_write2_b32 v130, v139, v135 offset0:76 offset1:142
	v_perm_b32 v130, v207, v163, s71
	v_perm_b32 v131, v146, v156, s71
	v_perm_b32 v132, v142, v147, s71
	v_perm_b32 v133, v135, v139, s71
	v_add_u32_e32 v134, v185, v179
	ds_write_b128 v134, v[130:133] offset:16896
	v_perm_b32 v130, v207, v163, s62
	v_perm_b32 v131, v146, v156, s62
	v_perm_b32 v132, v142, v147, s62
	v_perm_b32 v133, v135, v139, s62
	ds_write_b128 v134, v[130:133] offset:16976
	s_and_saveexec_b64 s[0:1], s[40:41]
	s_cbranch_execz .LBB0_301
	s_waitcnt lgkmcnt(11)
	v_exp_f32_e32 v130, v242
	s_waitcnt lgkmcnt(4)
	v_exp_f32_e32 v131, v136
	ds_write_b64 v187, v[130:131] offset:27136

.LBB0_309:
	s_add_i32 s0, s24, 3
	s_min_i32 s0, s0, s20
	s_lshl_b32 s0, s0, 5
	v_add_u32_e32 v4, s0, v56
	v_ashrrev_i32_e32 v5, 31, v4
	v_lshlrev_b64 v[4:5], 11, v[4:5]
	v_lshl_add_u64 v[4:5], v[4:5], 0, v[58:59]
	v_lshl_add_u64 v[6:7], v[4:5], 2, s[74:75]
	v_lshlrev_b64 v[4:5], 1, v[4:5]
	v_add_co_u32_e32 v10, vcc, s69, v6
	v_lshl_add_u64 v[8:9], s[64:65], 0, v[4:5]
	s_nop 0
	v_addc_co_u32_e32 v11, vcc, 0, v7, vcc
	v_lshlrev_b32_e32 v162, 16, v193
	v_and_b32_e32 v163, 0xffff0000, v193
	v_lshl_add_u64 v[4:5], s[72:73], 0, v[4:5]
	global_load_dwordx2 v[68:69], v[6:7], off
	global_load_dword v193, v[8:9], off
	global_load_dword v201, v[4:5], off
	global_load_dwordx2 v[104:105], v[10:11], off
	v_add_co_u32_e32 v10, vcc, s69, v8
	v_lshlrev_b32_e32 v244, 16, v194
	s_nop 0
	v_addc_co_u32_e32 v11, vcc, 0, v9, vcc
	v_add_co_u32_e32 v12, vcc, s69, v4
	v_and_b32_e32 v245, 0xffff0000, v194
	s_nop 0
	v_addc_co_u32_e32 v13, vcc, 0, v5, vcc
	v_add_co_u32_e32 v14, vcc, s66, v6
	v_lshlrev_b32_e32 v246, 16, v195
	s_nop 0
	v_addc_co_u32_e32 v15, vcc, 0, v7, vcc
	v_add_co_u32_e32 v16, vcc, s66, v8
	v_and_b32_e32 v247, 0xffff0000, v195
	s_nop 0
	v_addc_co_u32_e32 v17, vcc, 0, v9, vcc
	v_add_co_u32_e32 v18, vcc, s66, v4
	v_lshlrev_b32_e32 v156, 16, v191
	s_nop 0
	v_addc_co_u32_e32 v19, vcc, 0, v5, vcc
	v_and_b32_e32 v157, 0xffff0000, v191
	v_lshlrev_b32_e32 v154, 16, v190
	v_and_b32_e32 v155, 0xffff0000, v190
	global_load_dword v194, v[10:11], off offset:-4096
	global_load_dword v215, v[12:13], off offset:-4096
	global_load_dword v202, v[12:13], off
	global_load_dword v191, v[16:17], off offset:-4096
	global_load_dword v200, v[18:19], off offset:-4096
	global_load_dword v197, v[18:19], off
	global_load_dword v190, v[16:17], off
	global_load_dword v195, v[10:11], off
	v_add_co_u32_e32 v10, vcc, s63, v6
	v_lshlrev_b32_e32 v152, 16, v192
	s_nop 0
	v_addc_co_u32_e32 v11, vcc, 0, v7, vcc
	v_add_co_u32_e32 v12, vcc, s47, v6
	v_and_b32_e32 v153, 0xffff0000, v192
	s_nop 0
	v_addc_co_u32_e32 v13, vcc, 0, v7, vcc
	v_add_co_u32_e32 v16, vcc, s3, v6
	v_lshlrev_b32_e32 v150, 16, v189
	s_nop 0
	v_addc_co_u32_e32 v17, vcc, 0, v7, vcc
	global_load_dwordx2 v[76:77], v[14:15], off
	global_load_dwordx2 v[72:73], v[10:11], off
	global_load_dwordx2 v[70:71], v[12:13], off
	global_load_dwordx2 v[62:63], v[16:17], off
	v_add_co_u32_e32 v10, vcc, s63, v8
	v_and_b32_e32 v151, 0xffff0000, v189
	s_nop 0
	v_addc_co_u32_e32 v11, vcc, 0, v9, vcc
	v_add_co_u32_e32 v12, vcc, s63, v4
	s_ashr_i32 s1, s0, 31
	s_nop 0
	v_addc_co_u32_e32 v13, vcc, 0, v5, vcc
	v_add_co_u32_e32 v14, vcc, s67, v6
	global_load_dword v192, v[10:11], off offset:-4096
	global_load_dword v198, v[12:13], off offset:-4096
	global_load_dword v196, v[12:13], off
	global_load_dword v189, v[10:11], off
	v_addc_co_u32_e32 v15, vcc, 0, v7, vcc
	v_add_co_u32_e32 v6, vcc, s28, v6
	ds_bpermute_b32 v10, v218, v145
	s_nop 0
	v_addc_co_u32_e32 v7, vcc, 0, v7, vcc
	ds_bpermute_b32 v11, v218, v167
	v_add_co_u32_e32 v8, vcc, s33, v8
	v_lshlrev_b32_e32 v148, 16, v199
	s_nop 0
	v_addc_co_u32_e32 v9, vcc, 0, v9, vcc
	v_add_co_u32_e32 v4, vcc, s33, v4
	v_and_b32_e32 v149, 0xffff0000, v199
	s_nop 0
	v_addc_co_u32_e32 v5, vcc, 0, v5, vcc
	global_load_dwordx2 v[66:67], v[14:15], off
	global_load_dwordx2 v[64:65], v[6:7], off
	global_load_dword v199, v[8:9], off
	global_load_dword v225, v[4:5], off
	s_waitcnt lgkmcnt(1)
	v_add_f32_e32 v4, v145, v10
	s_waitcnt lgkmcnt(0)
	v_add_f32_e32 v5, v167, v11
	v_cndmask_b32_e64 v207, v4, v145, s[40:41]
	v_cndmask_b32_e64 v211, v5, v167, s[40:41]
	s_nop 0
	ds_bpermute_b32 v242, v219, v207
	ds_bpermute_b32 v243, v219, v211
	s_waitcnt lgkmcnt(1)
	v_add_f32_e32 v242, v207, v242
	s_waitcnt lgkmcnt(0)
	v_add_f32_e32 v243, v211, v243
	v_cndmask_b32_e64 v207, v207, v242, s[42:43]
	v_cndmask_b32_e64 v211, v211, v243, s[42:43]
	ds_bpermute_b32 v242, v220, v207
	v_sub_f32_e32 v207, v207, v145
	v_sub_f32_e32 v243, v211, v167
	v_add_f32_e32 v144, v144, v207
	v_add_f32_e32 v250, v143, v243
	v_exp_f32_e32 v248, v144
	ds_bpermute_b32 v143, v220, v211
	v_exp_f32_e64 v144, -v144
	v_exp_f32_e64 v211, -v250
	v_exp_f32_e32 v249, v250
	v_mul_f32_e32 v141, v141, v144
	v_mul_f32_e32 v144, v169, v211
	v_pk_mul_f32 v[162:163], v[248:249], v[162:163]
	v_cvt_pk_bf16_f32 v144, v141, v144
	v_add_f32_e32 v141, v142, v207
	v_add_f32_e32 v142, v147, v243
	v_cvt_pk_bf16_f32 v250, v162, v163
	v_exp_f32_e32 v162, v141
	v_exp_f32_e32 v163, v142
	v_exp_f32_e64 v248, -v141
	v_exp_f32_e64 v249, -v142
	v_add_u32_e32 v169, v46, v184
	v_pk_mul_f32 v[162:163], v[162:163], v[244:245]
	v_mov_b32_e32 v141, v139
	v_cvt_pk_bf16_f32 v142, v162, v163
	v_add_u32_e32 v163, 0x6c00, v169
	v_pk_mul_f32 v[140:141], v[140:141], v[248:249]
	ds_write2_b32 v163, v250, v142 offset1:66
	v_add_f32_e32 v142, v146, v207
	v_add_f32_e32 v147, v241, v243
	v_cvt_pk_bf16_f32 v162, v140, v141
	v_exp_f32_e32 v140, v142
	v_exp_f32_e32 v141, v147
	v_exp_f32_e64 v146, -v142
	v_exp_f32_e64 v147, -v147
	v_add_u32_e32 v139, 0x8c00, v169
	ds_write2_b32 v139, v144, v162 offset0:64 offset1:130
	v_mov_b32_e32 v139, v166
	v_pk_mul_f32 v[140:141], v[140:141], v[246:247]
	v_pk_mul_f32 v[138:139], v[138:139], v[146:147]
	v_add_f32_e32 v146, v239, v207
	v_add_f32_e32 v147, v240, v243
	v_cvt_pk_bf16_f32 v142, v140, v141
	v_exp_f32_e32 v140, v146
	v_exp_f32_e32 v141, v147
	v_exp_f32_e64 v146, -v146
	v_exp_f32_e64 v147, -v147
	v_cvt_pk_bf16_f32 v166, v138, v139
	v_pk_mul_f32 v[138:139], v[140:141], v[156:157]
	v_mul_f32_e32 v135, v135, v146
	v_cvt_pk_bf16_f32 v138, v138, v139
	v_mul_f32_e32 v139, v159, v147
	v_add_f32_e32 v140, v173, v207
	v_add_f32_e32 v141, v238, v243
	v_cvt_pk_bf16_f32 v146, v135, v139
	ds_write2_b32 v163, v142, v138 offset0:132 offset1:198
	v_exp_f32_e32 v138, v140
	v_exp_f32_e32 v139, v141
	v_exp_f32_e64 v140, -v140
	v_exp_f32_e64 v141, -v141
	v_add_u32_e32 v135, 0x8e00, v169
	ds_write2_b32 v135, v166, v146 offset0:68 offset1:134
	v_mov_b32_e32 v135, v137
	v_pk_mul_f32 v[138:139], v[138:139], v[154:155]
	v_pk_mul_f32 v[134:135], v[134:135], v[140:141]
	v_add_f32_e32 v137, v171, v207
	v_add_f32_e32 v140, v172, v243
	v_cvt_pk_bf16_f32 v142, v138, v139
	v_exp_f32_e32 v138, v137
	v_exp_f32_e32 v139, v140
	v_cvt_pk_bf16_f32 v141, v134, v135
	v_exp_f32_e64 v134, -v137
	v_exp_f32_e64 v135, -v140
	v_mov_b32_e32 v137, v131
	v_pk_mul_f32 v[138:139], v[138:139], v[152:153]
	v_add_u32_e32 v131, 0x9000, v169
	v_pk_mul_f32 v[134:135], v[136:137], v[134:135]
	v_add_f32_e32 v136, v168, v207
	v_add_f32_e32 v137, v170, v243
	v_cvt_pk_bf16_f32 v138, v138, v139
	v_cvt_pk_bf16_f32 v139, v134, v135
	v_exp_f32_e32 v134, v136
	v_exp_f32_e32 v135, v137
	v_exp_f32_e64 v136, -v136
	v_exp_f32_e64 v137, -v137
	ds_write2_b32 v131, v141, v139 offset0:72 offset1:138
	v_mov_b32_e32 v131, v133
	v_add_u32_e32 v140, 0x7000, v169
	v_pk_mul_f32 v[134:135], v[134:135], v[150:151]
	v_pk_mul_f32 v[130:131], v[130:131], v[136:137]
	v_add_f32_e32 v133, v145, v207
	v_add_f32_e32 v136, v167, v243
	ds_write2_b32 v140, v142, v138 offset0:8 offset1:74
	v_cvt_pk_bf16_f32 v138, v134, v135
	v_exp_f32_e32 v134, v133
	v_exp_f32_e32 v135, v136
	v_cvt_pk_bf16_f32 v137, v130, v131
	v_exp_f32_e64 v130, -v133
	v_exp_f32_e64 v131, -v136
	v_mov_b32_e32 v133, v158
	v_pk_mul_f32 v[134:135], v[134:135], v[148:149]
	v_pk_mul_f32 v[130:131], v[132:133], v[130:131]
	v_cvt_pk_bf16_f32 v134, v134, v135
	v_cvt_pk_bf16_f32 v135, v130, v131
	v_add_u32_e32 v130, 0x9200, v169
	ds_write2_b32 v140, v138, v134 offset0:140 offset1:206
	ds_write2_b32 v130, v137, v135 offset0:76 offset1:142
	v_perm_b32 v130, v162, v144, s71
	v_perm_b32 v131, v146, v166, s71
	v_perm_b32 v132, v139, v141, s71
	v_perm_b32 v133, v135, v137, s71
	v_add_u32_e32 v134, v48, v179
	ds_write_b128 v134, v[130:133] offset:44544
	v_perm_b32 v130, v162, v144, s62
	v_perm_b32 v131, v146, v166, s62
	v_perm_b32 v132, v139, v141, s62
	v_perm_b32 v133, v135, v137, s62
	ds_write_b128 v134, v[130:133] offset:44624
	s_and_saveexec_b64 s[0:1], s[40:41]
	s_cbranch_execz .LBB0_290
	s_waitcnt lgkmcnt(11)
	v_exp_f32_e32 v130, v242
	s_waitcnt lgkmcnt(10)
	v_exp_f32_e32 v131, v143
	v_add_u32_e32 v132, v48, v186
	ds_write_b64 v132, v[130:131] offset:54784
	s_branch .LBB0_290

.LBB0_312:
	s_andn2_b64 vcc, exec, s[0:1]
	s_cbranch_vccnz .LBB0_324
	s_and_b64 vcc, exec, s[38:39]
	s_cbranch_vccnz .LBB0_324
	s_and_b32 s0, s15, 0xffffffc0
	s_lshl_b32 s1, s0, 2
	s_waitcnt lgkmcnt(0)
	v_lshrrev_b32_e32 v3, 2, v161
	s_add_i32 s8, s1, 0
	s_waitcnt vmcnt(0)
	v_bfe_u32 v5, v161, 2, 2
	v_bitop3_b32 v3, v47, v3, 3 bitop3:0x78
	v_lshlrev_b32_e32 v4, 2, v0
	v_readlane_b32 s10, v255, 1
	v_lshlrev_b32_e32 v1, 2, v47
	v_lshlrev_b32_e32 v173, 3, v3
	v_bitop3_b32 v3, v47, v5, 4 bitop3:0x36
	s_add_i32 s8, s8, 0x15800
	v_readlane_b32 s11, v255, 2
	s_mov_b32 s12, s10
	s_ashr_i32 s1, s0, 31
	v_lshlrev_b32_e32 v172, 3, v47
	v_lshlrev_b32_e32 v175, 3, v3
	v_lshrrev_b32_e32 v229, 1, v47
	v_bfe_u32 v230, v161, 2, 2
	v_xor_b32_e32 v229, v229, v230
	v_and_b32_e32 v230, 1, v47
	v_lshlrev_b32_e32 v230, 3, v230
	v_lshl_add_u32 v173, v229, 4, v230
	v_xor_b32_e32 v175, 32, v173
	v_lshrrev_b32_e32 v229, 2, v174
	v_mul_u32_u24_e32 v228, 0x4400, v229
	v_bfe_u32 v229, v174, 4, 2
	v_and_b32_e32 v230, 3, v174
	v_xor_b32_e32 v229, v229, v230
	v_lshl_add_u32 v228, v229, 4, v228
	v_add_u32_e32 v177, s8, v4
	s_movk_i32 s8, 0x108
	v_cmp_gt_u32_e64 s[38:39], v1, v0
	v_cmp_lt_u32_e64 s[40:41], v1, v0
	v_or_b32_e32 v3, 2, v1
	v_or_b32_e32 v1, 3, v1
	v_readlane_b32 s16, v251, 55
	s_lshl_b32 s10, s10, 9
	s_and_b32 s9, s15, 0x3ffffc0
	s_lshl_b32 s11, s12, 6
	v_mad_u32_u24 v179, v0, s8, v172
	v_cmp_gt_u32_e64 s[44:45], v1, v0
	s_movk_i32 s8, 0x50
	v_mov_b32_e32 v1, 0x500
	s_lshl_b64 s[0:1], s[0:1], 2
	v_readlane_b32 s20, v251, 59
	v_mad_u32_u24 v183, v0, s8, v1
	v_readlane_b32 s21, v251, 60
	s_add_u32 s8, s20, s0
	v_or_b32_e32 v7, s9, v0
	s_addc_u32 s9, s21, s1
	v_mov_b32_e32 v5, v2
	v_lshlrev_b32_e32 v6, 10, v47
	v_readlane_b32 s24, v251, 63
	v_readlane_b32 s25, v252, 0
	v_readlane_b32 s26, v252, 1
	v_readlane_b32 s27, v252, 2
	v_lshl_add_u64 v[4:5], s[8:9], 0, v[4:5]
	v_lshlrev_b32_e32 v8, 12, v47
	v_mov_b32_e32 v9, v2
	v_and_b32_e32 v176, 48, v161
	v_mul_u32_u24_e32 v178, 0x108, v0
	v_add_u32_e32 v180, 0x1080, v179
	v_cmp_gt_u32_e64 s[42:43], v3, v0
	v_lshlrev_b32_e32 v181, 6, v7
	v_mul_u32_u24_e32 v182, 0x50, v0
	v_mul_u32_u24_e32 v184, 0x1040, v47
	v_mul_u32_u24_e32 v185, 0x410, v3
	v_lshl_add_u64 v[166:167], v[4:5], 0, v[8:9]
	v_lshlrev_b32_e32 v168, 2, v0
	v_lshlrev_b32_e32 v170, 2, v6
	s_mov_b32 s12, s2
	s_mov_b32 s24, 0x10000
	s_mov_b32 s25, 0x14000
	s_mov_b32 s26, 0x18000
	s_mov_b32 s27, 0x1c000
	v_readlane_b32 s17, v251, 56
	v_readlane_b32 s18, v251, 57
	v_readlane_b32 s19, v251, 58
	v_readlane_b32 s22, v251, 61
	v_readlane_b32 s23, v251, 62
	v_readlane_b32 s28, v252, 3
	v_readlane_b32 s29, v252, 4
	v_readlane_b32 s30, v252, 5
	v_readlane_b32 s31, v252, 6
	s_branch .LBB0_316

.LBB0_316:
	v_readlane_b32 s100, v251, 37
	v_readlane_b32 s101, v251, 38
	s_lshr_b32 s98, s12, 4
	s_mul_i32 s99, s98, 0x810
	s_sub_i32 s98, s98, 4
	s_lshl_b32 s98, s98, 3
	s_addk_i32 s98, 0x2040
	s_cmp_lt_i32 s12, 64
	s_cselect_b32 s98, s99, s98
	s_lshl_b32 s98, s98, 1
	s_and_b32 s99, s12, 15
	s_mul_i32 s99, s99, 0x440000
	s_add_i32 s98, s98, s99
	s_mul_i32 s99, s14, 0x110000
	s_add_i32 s98, s98, s99
	s_add_u32 s98, s100, s98
	s_addc_u32 s99, s101, 0
	s_cmp_lt_i32 s12, 64
	s_cselect_b64 s[8:9], -1, 0
	s_and_b32 s15, s12, -16
	s_sub_i32 s16, s15, 64
	s_and_b32 s13, s12, 15
	s_and_b64 vcc, exec, s[8:9]
	s_cbranch_vccnz .LBB0_318
	s_add_i32 s17, s16, s10
	s_or_b32 s18, s17, s13
	s_ashr_i32 s19, s18, 31
	s_lshl_b64 s[18:19], s[18:19], 17
	v_lshl_add_u64 v[0:1], v[166:167], 0, s[18:19]
	v_add_co_u32_e32 v36, vcc, s66, v0
	global_load_dword v4, v[0:1], off
	global_load_dword v5, v[0:1], off offset:1024
	global_load_dword v8, v[0:1], off offset:64
	global_load_dword v9, v[0:1], off offset:1088
	global_load_dword v12, v[0:1], off offset:128
	global_load_dword v13, v[0:1], off offset:1152
	global_load_dword v17, v[0:1], off offset:1216
	global_load_dword v16, v[0:1], off offset:192
	global_load_dword v6, v[0:1], off offset:2048
	global_load_dword v7, v[0:1], off offset:3072
	global_load_dword v10, v[0:1], off offset:2112
	global_load_dword v11, v[0:1], off offset:3136
	global_load_dword v14, v[0:1], off offset:2176
	global_load_dword v15, v[0:1], off offset:3200
	global_load_dword v19, v[0:1], off offset:3264
	global_load_dword v18, v[0:1], off offset:2240
	v_addc_co_u32_e32 v37, vcc, 0, v1, vcc
	v_add_co_u32_e32 v52, vcc, s47, v0
	global_load_dword v20, v[36:37], off
	global_load_dword v21, v[36:37], off offset:1024
	global_load_dword v24, v[36:37], off offset:64
	global_load_dword v25, v[36:37], off offset:1088
	global_load_dword v28, v[36:37], off offset:128
	global_load_dword v29, v[36:37], off offset:1152
	global_load_dword v33, v[36:37], off offset:1216
	global_load_dword v32, v[36:37], off offset:192
	global_load_dword v22, v[36:37], off offset:2048
	global_load_dword v23, v[36:37], off offset:3072
	global_load_dword v26, v[36:37], off offset:2112
	global_load_dword v27, v[36:37], off offset:3136
	global_load_dword v30, v[36:37], off offset:2176
	global_load_dword v31, v[36:37], off offset:3200
	global_load_dword v35, v[36:37], off offset:3264
	global_load_dword v34, v[36:37], off offset:2240
	v_addc_co_u32_e32 v53, vcc, 0, v1, vcc
	v_add_co_u32_e32 v68, vcc, s67, v0
	global_load_dword v36, v[52:53], off
	global_load_dword v37, v[52:53], off offset:1024
	global_load_dword v40, v[52:53], off offset:64
	global_load_dword v41, v[52:53], off offset:1088
	global_load_dword v44, v[52:53], off offset:128
	global_load_dword v45, v[52:53], off offset:1152
	global_load_dword v49, v[52:53], off offset:1216
	global_load_dword v48, v[52:53], off offset:192
	global_load_dword v38, v[52:53], off offset:2048
	global_load_dword v39, v[52:53], off offset:3072
	global_load_dword v42, v[52:53], off offset:2112
	global_load_dword v43, v[52:53], off offset:3136
	global_load_dword v46, v[52:53], off offset:2176
	global_load_dword v47, v[52:53], off offset:3200
	global_load_dword v51, v[52:53], off offset:3264
	global_load_dword v50, v[52:53], off offset:2240
	v_addc_co_u32_e32 v69, vcc, 0, v1, vcc
	v_add_co_u32_e32 v84, vcc, s24, v0
	global_load_dword v52, v[68:69], off
	global_load_dword v53, v[68:69], off offset:1024
	global_load_dword v56, v[68:69], off offset:64
	global_load_dword v57, v[68:69], off offset:1088
	global_load_dword v60, v[68:69], off offset:128
	global_load_dword v61, v[68:69], off offset:1152
	global_load_dword v65, v[68:69], off offset:1216
	global_load_dword v64, v[68:69], off offset:192
	global_load_dword v54, v[68:69], off offset:2048
	global_load_dword v55, v[68:69], off offset:3072
	global_load_dword v58, v[68:69], off offset:2112
	global_load_dword v59, v[68:69], off offset:3136
	global_load_dword v62, v[68:69], off offset:2176
	global_load_dword v63, v[68:69], off offset:3200
	global_load_dword v67, v[68:69], off offset:3264
	global_load_dword v66, v[68:69], off offset:2240
	v_addc_co_u32_e32 v85, vcc, 0, v1, vcc
	v_add_co_u32_e32 v100, vcc, s25, v0
	global_load_dword v68, v[84:85], off
	global_load_dword v69, v[84:85], off offset:1024
	global_load_dword v72, v[84:85], off offset:64
	global_load_dword v73, v[84:85], off offset:1088
	global_load_dword v76, v[84:85], off offset:128
	global_load_dword v77, v[84:85], off offset:1152
	global_load_dword v81, v[84:85], off offset:1216
	global_load_dword v80, v[84:85], off offset:192
	global_load_dword v70, v[84:85], off offset:2048
	global_load_dword v71, v[84:85], off offset:3072
	global_load_dword v74, v[84:85], off offset:2112
	global_load_dword v75, v[84:85], off offset:3136
	global_load_dword v78, v[84:85], off offset:2176
	global_load_dword v79, v[84:85], off offset:3200
	global_load_dword v83, v[84:85], off offset:3264
	global_load_dword v82, v[84:85], off offset:2240
	v_addc_co_u32_e32 v101, vcc, 0, v1, vcc
	v_add_co_u32_e32 v116, vcc, s26, v0
	global_load_dword v84, v[100:101], off
	global_load_dword v85, v[100:101], off offset:1024
	global_load_dword v88, v[100:101], off offset:64
	global_load_dword v89, v[100:101], off offset:1088
	global_load_dword v92, v[100:101], off offset:128
	global_load_dword v93, v[100:101], off offset:1152
	global_load_dword v97, v[100:101], off offset:1216
	global_load_dword v96, v[100:101], off offset:192
	global_load_dword v86, v[100:101], off offset:2048
	global_load_dword v87, v[100:101], off offset:3072
	global_load_dword v90, v[100:101], off offset:2112
	global_load_dword v91, v[100:101], off offset:3136
	global_load_dword v94, v[100:101], off offset:2176
	global_load_dword v95, v[100:101], off offset:3200
	global_load_dword v99, v[100:101], off offset:3264
	global_load_dword v98, v[100:101], off offset:2240
	v_addc_co_u32_e32 v117, vcc, 0, v1, vcc
	v_add_co_u32_e32 v0, vcc, s27, v0
	global_load_dword v100, v[116:117], off
	global_load_dword v101, v[116:117], off offset:1024
	global_load_dword v104, v[116:117], off offset:64
	global_load_dword v105, v[116:117], off offset:1088
	global_load_dword v108, v[116:117], off offset:128
	global_load_dword v109, v[116:117], off offset:1152
	global_load_dword v113, v[116:117], off offset:1216
	global_load_dword v112, v[116:117], off offset:192
	global_load_dword v102, v[116:117], off offset:2048
	global_load_dword v103, v[116:117], off offset:3072
	global_load_dword v106, v[116:117], off offset:2112
	global_load_dword v107, v[116:117], off offset:3136
	global_load_dword v110, v[116:117], off offset:2176
	global_load_dword v111, v[116:117], off offset:3200
	global_load_dword v115, v[116:117], off offset:3264
	global_load_dword v114, v[116:117], off offset:2240
	v_addc_co_u32_e32 v1, vcc, 0, v1, vcc
	global_load_dword v124, v[0:1], off
	global_load_dword v125, v[0:1], off offset:1024
	global_load_dword v116, v[0:1], off offset:64
	global_load_dword v117, v[0:1], off offset:1088
	global_load_dword v120, v[0:1], off offset:128
	global_load_dword v121, v[0:1], off offset:1152
	global_load_dword v129, v[0:1], off offset:1216
	global_load_dword v128, v[0:1], off offset:192
	global_load_dword v126, v[0:1], off offset:2048
	global_load_dword v127, v[0:1], off offset:3072
	global_load_dword v118, v[0:1], off offset:2112
	global_load_dword v119, v[0:1], off offset:3136
	global_load_dword v122, v[0:1], off offset:2176
	global_load_dword v123, v[0:1], off offset:3200
	global_load_dword v131, v[0:1], off offset:3264
	global_load_dword v130, v[0:1], off offset:2240
	s_branch .LBB0_319

.LBB0_320:
	s_waitcnt vmcnt(0) lgkmcnt(0)
	s_barrier
	s_add_i32 s19, s19, 1
	s_cmp_eq_u32 s18, s19
	s_cbranch_scc1 .LBB0_315
.LBB0_321:
	s_cmp_ge_u32 s19, s17
	s_cbranch_scc1 .Lscan_vdma_skip
	s_lshl_b32 s20, s19, 6
	s_add_u32 s100, s98, s20
	s_addc_u32 s101, s99, 0
	s_and_b32 s20, s19, 1
	s_lshl_b32 s20, s20, 14
	s_lshl_b32 s21, s14, 12
	s_add_i32 s20, s20, s21
	s_add_i32 m0, s20, 0xd800
	s_nop 0
	global_load_lds_dwordx4 v228, s[100:101]
	s_add_i32 m0, m0, 0x400
	s_add_u32 s100, s100, 0x44000
	s_addc_u32 s101, s101, 0
	global_load_lds_dwordx4 v228, s[100:101]
	s_add_i32 m0, m0, 0x400
	s_add_u32 s100, s100, 0x44000
	s_addc_u32 s101, s101, 0
	global_load_lds_dwordx4 v228, s[100:101]
	s_add_i32 m0, m0, 0x400
	s_add_u32 s100, s100, 0x44000
	s_addc_u32 s101, s101, 0
	global_load_lds_dwordx4 v228, s[100:101]
